# all four GEMM K-loops: first eight MFMAs of each super-phase issued before the load-segment barrier
# baseline (speedup 1.0000x reference)
.LBB0_88:
	ds_read_b128 v[146:149], v162
	ds_read_b128 v[150:153], v162 offset:1024
	ds_read_b128 v[154:157], v162 offset:2048
	ds_read_b128 v[166:169], v162 offset:3072
	ds_read_b128 v[170:173], v163
	ds_read_b128 v[174:177], v163 offset:1024
	ds_read_b128 v[178:181], v163 offset:2048
	ds_read_b128 v[182:185], v163 offset:3072
	s_add_u32 s8, s6, 0xfffc0080
	s_addc_u32 s9, s7, -1
	s_cmp_eq_u32 s54, 12
	s_cselect_b32 s35, s5, s9
	s_cselect_b32 s34, s10, s8
	s_cselect_b32 s9, s11, s53
	s_cselect_b32 s8, s26, s27
	v_lshl_add_u64 v[158:159], s[6:7], 0, v[138:139]
	s_add_i32 m0, s19, 0xc000
	ds_read_b128 v[190:193], v164
	ds_read_b128 v[194:197], v164 offset:1024
	ds_read_b128 v[198:201], v164 offset:2048
	ds_read_b128 v[202:205], v164 offset:3072
	ds_read_b128 v[206:209], v164 offset:4096
	ds_read_b128 v[210:213], v164 offset:5120
	ds_read_b128 v[214:217], v164 offset:6144
	ds_read_b128 v[218:221], v164 offset:7168
	global_load_lds_dwordx4 v[158:159], off
	v_lshl_add_u64 v[158:159], s[6:7], 0, v[140:141]
	s_add_i32 m0, s19, 0xe000
	s_nop 0
	global_load_lds_dwordx4 v[158:159], off
	s_waitcnt vmcnt(8)
	s_waitcnt lgkmcnt(0)
	v_mfma_f32_16x16x32_bf16 v[124:127], v[146:149], v[190:193], v[124:127]
	v_mfma_f32_16x16x32_bf16 v[120:123], v[154:157], v[190:193], v[120:123]
	v_mfma_f32_16x16x32_bf16 v[108:111], v[146:149], v[198:201], v[108:111]
	v_mfma_f32_16x16x32_bf16 v[104:107], v[154:157], v[198:201], v[104:107]
	v_mfma_f32_16x16x32_bf16 v[92:95], v[146:149], v[206:209], v[92:95]
	v_mfma_f32_16x16x32_bf16 v[88:91], v[154:157], v[206:209], v[88:91]
	v_mfma_f32_16x16x32_bf16 v[76:79], v[146:149], v[214:217], v[76:79]
	v_mfma_f32_16x16x32_bf16 v[72:75], v[154:157], v[214:217], v[72:75]
	s_barrier
	s_setprio 1
	v_mfma_f32_16x16x32_bf16 v[124:127], v[150:153], v[194:197], v[124:127]
	v_mfma_f32_16x16x32_bf16 v[120:123], v[166:169], v[194:197], v[120:123]
	v_mfma_f32_16x16x32_bf16 v[108:111], v[150:153], v[202:205], v[108:111]
	v_mfma_f32_16x16x32_bf16 v[104:107], v[166:169], v[202:205], v[104:107]
	v_mfma_f32_16x16x32_bf16 v[92:95], v[150:153], v[210:213], v[92:95]
	v_mfma_f32_16x16x32_bf16 v[88:91], v[166:169], v[210:213], v[88:91]
	v_mfma_f32_16x16x32_bf16 v[76:79], v[150:153], v[218:221], v[76:79]
	v_mfma_f32_16x16x32_bf16 v[72:75], v[166:169], v[218:221], v[72:75]
	s_setprio 0
	s_setprio 1
	v_mfma_f32_16x16x32_bf16 v[116:119], v[170:173], v[190:193], v[116:119]
	v_mfma_f32_16x16x32_bf16 v[112:115], v[178:181], v[190:193], v[112:115]
	v_mfma_f32_16x16x32_bf16 v[100:103], v[170:173], v[198:201], v[100:103]
	v_mfma_f32_16x16x32_bf16 v[96:99], v[178:181], v[198:201], v[96:99]
	v_mfma_f32_16x16x32_bf16 v[84:87], v[170:173], v[206:209], v[84:87]
	v_mfma_f32_16x16x32_bf16 v[80:83], v[178:181], v[206:209], v[80:83]
	v_mfma_f32_16x16x32_bf16 v[68:71], v[170:173], v[214:217], v[68:71]
	v_mfma_f32_16x16x32_bf16 v[64:67], v[178:181], v[214:217], v[64:67]
	v_mfma_f32_16x16x32_bf16 v[116:119], v[174:177], v[194:197], v[116:119]
	v_mfma_f32_16x16x32_bf16 v[112:115], v[182:185], v[194:197], v[112:115]
	v_mfma_f32_16x16x32_bf16 v[100:103], v[174:177], v[202:205], v[100:103]
	v_mfma_f32_16x16x32_bf16 v[96:99], v[182:185], v[202:205], v[96:99]
	v_mfma_f32_16x16x32_bf16 v[84:87], v[174:177], v[210:213], v[84:87]
	v_mfma_f32_16x16x32_bf16 v[80:83], v[182:185], v[210:213], v[80:83]
	v_mfma_f32_16x16x32_bf16 v[68:71], v[174:177], v[218:221], v[68:71]
	v_mfma_f32_16x16x32_bf16 v[64:67], v[182:185], v[218:221], v[64:67]
	s_setprio 0
	s_barrier
	s_add_i32 s55, s45, s33
	v_lshl_add_u64 v[158:159], s[8:9], 0, v[130:131]
	s_mov_b32 m0, s55
	ds_read_b128 v[190:193], v164 offset:16384
	ds_read_b128 v[194:197], v164 offset:17408
	ds_read_b128 v[198:201], v164 offset:18432
	ds_read_b128 v[202:205], v164 offset:19456
	ds_read_b128 v[206:209], v164 offset:20480
	ds_read_b128 v[210:213], v164 offset:21504
	ds_read_b128 v[214:217], v164 offset:22528
	ds_read_b128 v[218:221], v164 offset:23552
	global_load_lds_dwordx4 v[158:159], off
	s_add_i32 m0, s55, 0x2000
	s_add_u32 s56, s8, 0x40000
	v_lshl_add_u64 v[186:187], s[8:9], 0, v[134:135]
	s_addc_u32 s57, s9, 0
	s_add_i32 s55, s46, s33
	global_load_lds_dwordx4 v[186:187], off
	v_lshl_add_u64 v[222:223], s[56:57], 0, v[130:131]
	s_mov_b32 m0, s55
	v_lshl_add_u64 v[224:225], s[34:35], 0, v[132:133]
	global_load_lds_dwordx4 v[222:223], off
	v_lshl_add_u64 v[222:223], s[56:57], 0, v[134:135]
	s_add_i32 m0, s55, 0x2000
	s_nop 0
	global_load_lds_dwordx4 v[222:223], off
	v_lshl_add_u64 v[222:223], s[34:35], 0, v[128:129]
	s_mov_b32 m0, s19
	s_nop 0
	global_load_lds_dwordx4 v[222:223], off
	s_mov_b32 m0, s36
	s_nop 0
	global_load_lds_dwordx4 v[224:225], off
	s_waitcnt vmcnt(8)
	s_waitcnt lgkmcnt(0)
	v_mfma_f32_16x16x32_bf16 v[60:63], v[146:149], v[190:193], v[60:63]
	v_mfma_f32_16x16x32_bf16 v[56:59], v[154:157], v[190:193], v[56:59]
	v_mfma_f32_16x16x32_bf16 v[44:47], v[146:149], v[198:201], v[44:47]
	v_mfma_f32_16x16x32_bf16 v[40:43], v[154:157], v[198:201], v[40:43]
	v_mfma_f32_16x16x32_bf16 v[28:31], v[146:149], v[206:209], v[28:31]
	v_mfma_f32_16x16x32_bf16 v[24:27], v[154:157], v[206:209], v[24:27]
	v_mfma_f32_16x16x32_bf16 v[12:15], v[146:149], v[214:217], v[12:15]
	v_mfma_f32_16x16x32_bf16 v[8:11], v[154:157], v[214:217], v[8:11]
	s_barrier
	s_setprio 1
	v_mfma_f32_16x16x32_bf16 v[60:63], v[150:153], v[194:197], v[60:63]
	v_mfma_f32_16x16x32_bf16 v[56:59], v[166:169], v[194:197], v[56:59]
	v_mfma_f32_16x16x32_bf16 v[44:47], v[150:153], v[202:205], v[44:47]
	v_mfma_f32_16x16x32_bf16 v[40:43], v[166:169], v[202:205], v[40:43]
	v_mfma_f32_16x16x32_bf16 v[28:31], v[150:153], v[210:213], v[28:31]
	v_mfma_f32_16x16x32_bf16 v[24:27], v[166:169], v[210:213], v[24:27]
	v_mfma_f32_16x16x32_bf16 v[12:15], v[150:153], v[218:221], v[12:15]
	v_mfma_f32_16x16x32_bf16 v[8:11], v[166:169], v[218:221], v[8:11]
	s_setprio 0
	s_setprio 1
	v_mfma_f32_16x16x32_bf16 v[52:55], v[170:173], v[190:193], v[52:55]
	v_mfma_f32_16x16x32_bf16 v[48:51], v[178:181], v[190:193], v[48:51]
	v_mfma_f32_16x16x32_bf16 v[36:39], v[170:173], v[198:201], v[36:39]
	v_mfma_f32_16x16x32_bf16 v[32:35], v[178:181], v[198:201], v[32:35]
	v_mfma_f32_16x16x32_bf16 v[20:23], v[170:173], v[206:209], v[20:23]
	v_mfma_f32_16x16x32_bf16 v[16:19], v[178:181], v[206:209], v[16:19]
	v_mfma_f32_16x16x32_bf16 v[4:7], v[170:173], v[214:217], v[4:7]
	v_mfma_f32_16x16x32_bf16 v[0:3], v[178:181], v[214:217], v[0:3]
	v_mfma_f32_16x16x32_bf16 v[52:55], v[174:177], v[194:197], v[52:55]
	v_mfma_f32_16x16x32_bf16 v[48:51], v[182:185], v[194:197], v[48:51]
	v_mfma_f32_16x16x32_bf16 v[36:39], v[174:177], v[202:205], v[36:39]
	v_mfma_f32_16x16x32_bf16 v[32:35], v[182:185], v[202:205], v[32:35]
	v_mfma_f32_16x16x32_bf16 v[20:23], v[174:177], v[210:213], v[20:23]
	v_mfma_f32_16x16x32_bf16 v[16:19], v[182:185], v[210:213], v[16:19]
	v_mfma_f32_16x16x32_bf16 v[4:7], v[174:177], v[218:221], v[4:7]
	v_mfma_f32_16x16x32_bf16 v[0:3], v[182:185], v[218:221], v[0:3]
	s_setprio 0
	s_barrier
	s_add_i32 s55, 0, 0x18000
	v_add_u32_e32 v165, s55, v160
	s_add_i32 s56, 0, 0x1c000
	ds_read_b128 v[146:149], v165
	ds_read_b128 v[150:153], v165 offset:1024
	ds_read_b128 v[154:157], v165 offset:2048
	ds_read_b128 v[166:169], v165 offset:3072
	v_add_u32_e32 v165, s56, v160
	ds_read_b128 v[170:173], v165
	ds_read_b128 v[174:177], v165 offset:1024
	ds_read_b128 v[178:181], v165 offset:2048
	ds_read_b128 v[182:185], v165 offset:3072
	s_add_u32 s34, s34, 0x40000
	s_addc_u32 s35, s35, 0
	s_mov_b32 m0, s37
	v_lshl_add_u64 v[226:227], s[34:35], 0, v[128:129]
	ds_read_b128 v[190:193], v164 offset:32768
	ds_read_b128 v[194:197], v164 offset:33792
	ds_read_b128 v[198:201], v164 offset:34816
	ds_read_b128 v[202:205], v164 offset:35840
	ds_read_b128 v[206:209], v164 offset:36864
	ds_read_b128 v[210:213], v164 offset:37888
	ds_read_b128 v[214:217], v164 offset:38912
	ds_read_b128 v[218:221], v164 offset:39936
	global_load_lds_dwordx4 v[226:227], off
	v_lshl_add_u64 v[226:227], s[34:35], 0, v[132:133]
	s_mov_b32 m0, s38
	s_nop 0
	global_load_lds_dwordx4 v[226:227], off
	s_waitcnt vmcnt(8)
	s_waitcnt lgkmcnt(0)
	v_mfma_f32_16x16x32_bf16 v[124:127], v[146:149], v[190:193], v[124:127]
	v_mfma_f32_16x16x32_bf16 v[120:123], v[154:157], v[190:193], v[120:123]
	v_mfma_f32_16x16x32_bf16 v[108:111], v[146:149], v[198:201], v[108:111]
	v_mfma_f32_16x16x32_bf16 v[104:107], v[154:157], v[198:201], v[104:107]
	v_mfma_f32_16x16x32_bf16 v[92:95], v[146:149], v[206:209], v[92:95]
	v_mfma_f32_16x16x32_bf16 v[88:91], v[154:157], v[206:209], v[88:91]
	v_mfma_f32_16x16x32_bf16 v[76:79], v[146:149], v[214:217], v[76:79]
	v_mfma_f32_16x16x32_bf16 v[72:75], v[154:157], v[214:217], v[72:75]
	s_barrier
	s_setprio 1
	v_mfma_f32_16x16x32_bf16 v[124:127], v[150:153], v[194:197], v[124:127]
	v_mfma_f32_16x16x32_bf16 v[120:123], v[166:169], v[194:197], v[120:123]
	v_mfma_f32_16x16x32_bf16 v[108:111], v[150:153], v[202:205], v[108:111]
	v_mfma_f32_16x16x32_bf16 v[104:107], v[166:169], v[202:205], v[104:107]
	v_mfma_f32_16x16x32_bf16 v[92:95], v[150:153], v[210:213], v[92:95]
	v_mfma_f32_16x16x32_bf16 v[88:91], v[166:169], v[210:213], v[88:91]
	v_mfma_f32_16x16x32_bf16 v[76:79], v[150:153], v[218:221], v[76:79]
	v_mfma_f32_16x16x32_bf16 v[72:75], v[166:169], v[218:221], v[72:75]
	s_setprio 0
	s_setprio 1
	v_mfma_f32_16x16x32_bf16 v[116:119], v[170:173], v[190:193], v[116:119]
	v_mfma_f32_16x16x32_bf16 v[112:115], v[178:181], v[190:193], v[112:115]
	v_mfma_f32_16x16x32_bf16 v[100:103], v[170:173], v[198:201], v[100:103]
	v_mfma_f32_16x16x32_bf16 v[96:99], v[178:181], v[198:201], v[96:99]
	v_mfma_f32_16x16x32_bf16 v[84:87], v[170:173], v[206:209], v[84:87]
	v_mfma_f32_16x16x32_bf16 v[80:83], v[178:181], v[206:209], v[80:83]
	v_mfma_f32_16x16x32_bf16 v[68:71], v[170:173], v[214:217], v[68:71]
	v_mfma_f32_16x16x32_bf16 v[64:67], v[178:181], v[214:217], v[64:67]
	v_mfma_f32_16x16x32_bf16 v[116:119], v[174:177], v[194:197], v[116:119]
	v_mfma_f32_16x16x32_bf16 v[112:115], v[182:185], v[194:197], v[112:115]
	v_mfma_f32_16x16x32_bf16 v[100:103], v[174:177], v[202:205], v[100:103]
	v_mfma_f32_16x16x32_bf16 v[96:99], v[182:185], v[202:205], v[96:99]
	v_mfma_f32_16x16x32_bf16 v[84:87], v[174:177], v[210:213], v[84:87]
	v_mfma_f32_16x16x32_bf16 v[80:83], v[182:185], v[210:213], v[80:83]
	v_mfma_f32_16x16x32_bf16 v[68:71], v[174:177], v[218:221], v[68:71]
	v_mfma_f32_16x16x32_bf16 v[64:67], v[182:185], v[218:221], v[64:67]
	s_setprio 0
	s_barrier
	s_add_i32 s34, s55, s33
	v_lshl_add_u64 v[158:159], v[158:159], 0, s[20:21]
	s_mov_b32 m0, s34
	ds_read_b128 v[190:193], v164 offset:49152
	ds_read_b128 v[194:197], v164 offset:50176
	ds_read_b128 v[198:201], v164 offset:51200
	ds_read_b128 v[202:205], v164 offset:52224
	ds_read_b128 v[206:209], v164 offset:53248
	ds_read_b128 v[210:213], v164 offset:54272
	ds_read_b128 v[214:217], v164 offset:55296
	ds_read_b128 v[218:221], v164 offset:56320
	global_load_lds_dwordx4 v[158:159], off
	s_add_i32 m0, s34, 0x2000
	s_add_u32 s8, s8, 0x40080
	v_lshl_add_u64 v[158:159], v[186:187], 0, s[20:21]
	s_addc_u32 s9, s9, 0
	s_add_i32 s34, s56, s33
	global_load_lds_dwordx4 v[158:159], off
	v_lshl_add_u64 v[158:159], s[8:9], 0, v[130:131]
	s_mov_b32 m0, s34
	s_nop 0
	global_load_lds_dwordx4 v[158:159], off
	v_lshl_add_u64 v[158:159], s[8:9], 0, v[134:135]
	s_add_i32 m0, s34, 0x2000
	s_nop 0
	global_load_lds_dwordx4 v[158:159], off
	v_lshl_add_u64 v[158:159], v[222:223], 0, s[20:21]
	s_mov_b32 m0, s40
	s_nop 0
	global_load_lds_dwordx4 v[158:159], off
	v_lshl_add_u64 v[158:159], v[224:225], 0, s[20:21]
	s_mov_b32 m0, s41
	s_nop 0
	global_load_lds_dwordx4 v[158:159], off
	s_waitcnt vmcnt(8)
	s_waitcnt lgkmcnt(0)
	v_mfma_f32_16x16x32_bf16 v[60:63], v[146:149], v[190:193], v[60:63]
	v_mfma_f32_16x16x32_bf16 v[56:59], v[154:157], v[190:193], v[56:59]
	v_mfma_f32_16x16x32_bf16 v[44:47], v[146:149], v[198:201], v[44:47]
	v_mfma_f32_16x16x32_bf16 v[40:43], v[154:157], v[198:201], v[40:43]
	v_mfma_f32_16x16x32_bf16 v[28:31], v[146:149], v[206:209], v[28:31]
	v_mfma_f32_16x16x32_bf16 v[24:27], v[154:157], v[206:209], v[24:27]
	v_mfma_f32_16x16x32_bf16 v[12:15], v[146:149], v[214:217], v[12:15]
	v_mfma_f32_16x16x32_bf16 v[8:11], v[154:157], v[214:217], v[8:11]
	s_barrier
	s_setprio 1
	v_mfma_f32_16x16x32_bf16 v[60:63], v[150:153], v[194:197], v[60:63]
	v_mfma_f32_16x16x32_bf16 v[56:59], v[166:169], v[194:197], v[56:59]
	v_mfma_f32_16x16x32_bf16 v[44:47], v[150:153], v[202:205], v[44:47]
	v_mfma_f32_16x16x32_bf16 v[40:43], v[166:169], v[202:205], v[40:43]
	v_mfma_f32_16x16x32_bf16 v[28:31], v[150:153], v[210:213], v[28:31]
	v_mfma_f32_16x16x32_bf16 v[24:27], v[166:169], v[210:213], v[24:27]
	v_mfma_f32_16x16x32_bf16 v[12:15], v[150:153], v[218:221], v[12:15]
	v_mfma_f32_16x16x32_bf16 v[8:11], v[166:169], v[218:221], v[8:11]
	s_setprio 0
	s_setprio 1
	v_mfma_f32_16x16x32_bf16 v[52:55], v[170:173], v[190:193], v[52:55]
	v_mfma_f32_16x16x32_bf16 v[48:51], v[178:181], v[190:193], v[48:51]
	v_mfma_f32_16x16x32_bf16 v[36:39], v[170:173], v[198:201], v[36:39]
	v_mfma_f32_16x16x32_bf16 v[32:35], v[178:181], v[198:201], v[32:35]
	v_mfma_f32_16x16x32_bf16 v[20:23], v[170:173], v[206:209], v[20:23]
	v_mfma_f32_16x16x32_bf16 v[16:19], v[178:181], v[206:209], v[16:19]
	v_mfma_f32_16x16x32_bf16 v[4:7], v[170:173], v[214:217], v[4:7]
	v_mfma_f32_16x16x32_bf16 v[0:3], v[178:181], v[214:217], v[0:3]
	v_mfma_f32_16x16x32_bf16 v[52:55], v[174:177], v[194:197], v[52:55]
	v_mfma_f32_16x16x32_bf16 v[48:51], v[182:185], v[194:197], v[48:51]
	v_mfma_f32_16x16x32_bf16 v[36:39], v[174:177], v[202:205], v[36:39]
	v_mfma_f32_16x16x32_bf16 v[32:35], v[182:185], v[202:205], v[32:35]
	v_mfma_f32_16x16x32_bf16 v[20:23], v[174:177], v[210:213], v[20:23]
	v_mfma_f32_16x16x32_bf16 v[16:19], v[182:185], v[210:213], v[16:19]
	v_mfma_f32_16x16x32_bf16 v[4:7], v[174:177], v[218:221], v[4:7]
	v_mfma_f32_16x16x32_bf16 v[0:3], v[182:185], v[218:221], v[0:3]
	s_setprio 0
	s_barrier
	s_add_i32 s54, s54, 2
	s_add_u32 s6, s6, 0x100
	s_addc_u32 s7, s7, 0
	s_add_u32 s27, s27, 0x100
	s_addc_u32 s53, s53, 0
	s_cmp_gt_u32 s54, 13
	s_cbranch_scc0 .LBB0_88
	s_and_b64 vcc, exec, s[22:23]
	s_cbranch_vccz .LBB0_91
	s_barrier

.LBB0_630:
	v_add_u32_e32 v1, s47, v158
	ds_read_b128 v[174:177], v1
	ds_read_b128 v[178:181], v1 offset:1024
	ds_read_b128 v[182:185], v1 offset:2048
	ds_read_b128 v[190:193], v1 offset:3072
	v_add_u32_e32 v1, s48, v158
	s_add_u32 s53, s58, s54
	ds_read_b128 v[194:197], v1
	ds_read_b128 v[198:201], v1 offset:1024
	ds_read_b128 v[202:205], v1 offset:2048
	ds_read_b128 v[206:209], v1 offset:3072
	s_addc_u32 s57, s59, s55
	s_add_u32 s53, s53, 0x100
	s_addc_u32 s57, s57, 0
	s_add_u32 s60, s50, s54
	s_addc_u32 s61, s51, s55
	s_cmpk_eq_i32 s54, 0x700
	s_cselect_b32 s63, s21, s57
	s_cselect_b32 s62, s26, s53
	s_cselect_b32 s61, s19, s61
	s_cselect_b32 s60, s27, s60
	v_lshl_add_u64 v[2:3], v[148:149], 0, s[54:55]
	s_add_i32 m0, s38, 0xc000
	ds_read_b128 v[210:213], v169
	ds_read_b128 v[214:217], v169 offset:1024
	ds_read_b128 v[218:221], v169 offset:2048
	ds_read_b128 v[222:225], v169 offset:3072
	ds_read_b128 v[226:229], v169 offset:4096
	ds_read_b128 v[230:233], v169 offset:5120
	ds_read_b128 v[234:237], v169 offset:6144
	ds_read_b128 v[238:241], v169 offset:7168
	global_load_lds_dwordx4 v[2:3], off
	v_lshl_add_u64 v[2:3], v[150:151], 0, s[54:55]
	s_add_i32 m0, s38, 0xe000
	s_nop 0
	global_load_lds_dwordx4 v[2:3], off
	s_waitcnt vmcnt(8)
	s_waitcnt lgkmcnt(0)
	v_mfma_f32_16x16x32_bf16 v[128:131], v[174:177], v[210:213], v[128:131]
	v_mfma_f32_16x16x32_bf16 v[124:127], v[182:185], v[210:213], v[124:127]
	v_mfma_f32_16x16x32_bf16 v[112:115], v[174:177], v[218:221], v[112:115]
	v_mfma_f32_16x16x32_bf16 v[108:111], v[182:185], v[218:221], v[108:111]
	v_mfma_f32_16x16x32_bf16 v[96:99], v[174:177], v[226:229], v[96:99]
	v_mfma_f32_16x16x32_bf16 v[92:95], v[182:185], v[226:229], v[92:95]
	v_mfma_f32_16x16x32_bf16 v[80:83], v[174:177], v[234:237], v[80:83]
	v_mfma_f32_16x16x32_bf16 v[76:79], v[182:185], v[234:237], v[76:79]
	s_barrier
	s_setprio 1
	v_mfma_f32_16x16x32_bf16 v[128:131], v[178:181], v[214:217], v[128:131]
	v_mfma_f32_16x16x32_bf16 v[124:127], v[190:193], v[214:217], v[124:127]
	v_mfma_f32_16x16x32_bf16 v[112:115], v[178:181], v[222:225], v[112:115]
	v_mfma_f32_16x16x32_bf16 v[108:111], v[190:193], v[222:225], v[108:111]
	v_mfma_f32_16x16x32_bf16 v[96:99], v[178:181], v[230:233], v[96:99]
	v_mfma_f32_16x16x32_bf16 v[92:95], v[190:193], v[230:233], v[92:95]
	v_mfma_f32_16x16x32_bf16 v[80:83], v[178:181], v[238:241], v[80:83]
	v_mfma_f32_16x16x32_bf16 v[76:79], v[190:193], v[238:241], v[76:79]
	s_setprio 0
	s_setprio 1
	v_mfma_f32_16x16x32_bf16 v[120:123], v[194:197], v[210:213], v[120:123]
	v_mfma_f32_16x16x32_bf16 v[116:119], v[202:205], v[210:213], v[116:119]
	v_mfma_f32_16x16x32_bf16 v[104:107], v[194:197], v[218:221], v[104:107]
	v_mfma_f32_16x16x32_bf16 v[100:103], v[202:205], v[218:221], v[100:103]
	v_mfma_f32_16x16x32_bf16 v[88:91], v[194:197], v[226:229], v[88:91]
	v_mfma_f32_16x16x32_bf16 v[84:87], v[202:205], v[226:229], v[84:87]
	v_mfma_f32_16x16x32_bf16 v[72:75], v[194:197], v[234:237], v[72:75]
	v_mfma_f32_16x16x32_bf16 v[68:71], v[202:205], v[234:237], v[68:71]
	v_mfma_f32_16x16x32_bf16 v[120:123], v[198:201], v[214:217], v[120:123]
	v_mfma_f32_16x16x32_bf16 v[116:119], v[206:209], v[214:217], v[116:119]
	v_mfma_f32_16x16x32_bf16 v[104:107], v[198:201], v[222:225], v[104:107]
	v_mfma_f32_16x16x32_bf16 v[100:103], v[206:209], v[222:225], v[100:103]
	v_mfma_f32_16x16x32_bf16 v[88:91], v[198:201], v[230:233], v[88:91]
	v_mfma_f32_16x16x32_bf16 v[84:87], v[206:209], v[230:233], v[84:87]
	v_mfma_f32_16x16x32_bf16 v[72:75], v[198:201], v[238:241], v[72:75]
	v_mfma_f32_16x16x32_bf16 v[68:71], v[206:209], v[238:241], v[68:71]
	s_setprio 0
	s_barrier
	s_add_i32 s53, s47, s33
	v_lshl_add_u64 v[186:187], s[60:61], 0, v[134:135]
	s_mov_b32 m0, s53
	ds_read_b128 v[210:213], v169 offset:16384
	ds_read_b128 v[214:217], v169 offset:17408
	ds_read_b128 v[218:221], v169 offset:18432
	ds_read_b128 v[222:225], v169 offset:19456
	ds_read_b128 v[226:229], v169 offset:20480
	ds_read_b128 v[230:233], v169 offset:21504
	ds_read_b128 v[234:237], v169 offset:22528
	ds_read_b128 v[238:241], v169 offset:23552
	global_load_lds_dwordx4 v[186:187], off
	s_add_i32 m0, s53, 0x2000
	s_add_u32 s64, s60, 0x40000
	v_lshl_add_u64 v[242:243], s[60:61], 0, v[138:139]
	s_addc_u32 s65, s61, 0
	s_add_i32 s53, s48, s33
	global_load_lds_dwordx4 v[242:243], off
	v_lshl_add_u64 v[2:3], s[64:65], 0, v[134:135]
	s_mov_b32 m0, s53
	v_lshl_add_u64 v[244:245], s[62:63], 0, v[132:133]
	global_load_lds_dwordx4 v[2:3], off
	v_lshl_add_u64 v[2:3], s[64:65], 0, v[138:139]
	s_add_i32 m0, s53, 0x2000
	v_lshl_add_u64 v[246:247], s[62:63], 0, v[136:137]
	global_load_lds_dwordx4 v[2:3], off
	s_mov_b32 m0, s38
	s_nop 0
	global_load_lds_dwordx4 v[244:245], off
	s_mov_b32 m0, s39
	s_nop 0
	global_load_lds_dwordx4 v[246:247], off
	s_waitcnt vmcnt(8)
	s_waitcnt lgkmcnt(0)
	v_mfma_f32_16x16x32_bf16 v[64:67], v[174:177], v[210:213], v[64:67]
	v_mfma_f32_16x16x32_bf16 v[60:63], v[182:185], v[210:213], v[60:63]
	v_mfma_f32_16x16x32_bf16 v[48:51], v[174:177], v[218:221], v[48:51]
	v_mfma_f32_16x16x32_bf16 v[44:47], v[182:185], v[218:221], v[44:47]
	v_mfma_f32_16x16x32_bf16 v[32:35], v[174:177], v[226:229], v[32:35]
	v_mfma_f32_16x16x32_bf16 v[28:31], v[182:185], v[226:229], v[28:31]
	v_mfma_f32_16x16x32_bf16 v[16:19], v[174:177], v[234:237], v[16:19]
	v_mfma_f32_16x16x32_bf16 v[12:15], v[182:185], v[234:237], v[12:15]
	s_barrier
	s_setprio 1
	v_mfma_f32_16x16x32_bf16 v[64:67], v[178:181], v[214:217], v[64:67]
	v_mfma_f32_16x16x32_bf16 v[60:63], v[190:193], v[214:217], v[60:63]
	v_mfma_f32_16x16x32_bf16 v[48:51], v[178:181], v[222:225], v[48:51]
	v_mfma_f32_16x16x32_bf16 v[44:47], v[190:193], v[222:225], v[44:47]
	v_mfma_f32_16x16x32_bf16 v[32:35], v[178:181], v[230:233], v[32:35]
	v_mfma_f32_16x16x32_bf16 v[28:31], v[190:193], v[230:233], v[28:31]
	v_mfma_f32_16x16x32_bf16 v[16:19], v[178:181], v[238:241], v[16:19]
	v_mfma_f32_16x16x32_bf16 v[12:15], v[190:193], v[238:241], v[12:15]
	s_setprio 0
	s_setprio 1
	v_mfma_f32_16x16x32_bf16 v[56:59], v[194:197], v[210:213], v[56:59]
	v_mfma_f32_16x16x32_bf16 v[52:55], v[202:205], v[210:213], v[52:55]
	v_mfma_f32_16x16x32_bf16 v[40:43], v[194:197], v[218:221], v[40:43]
	v_mfma_f32_16x16x32_bf16 v[36:39], v[202:205], v[218:221], v[36:39]
	v_mfma_f32_16x16x32_bf16 v[24:27], v[194:197], v[226:229], v[24:27]
	v_mfma_f32_16x16x32_bf16 v[20:23], v[202:205], v[226:229], v[20:23]
	v_mfma_f32_16x16x32_bf16 v[8:11], v[194:197], v[234:237], v[8:11]
	v_mfma_f32_16x16x32_bf16 v[2:5], v[202:205], v[234:237], v[4:7]
	v_mfma_f32_16x16x32_bf16 v[56:59], v[198:201], v[214:217], v[56:59]
	v_mfma_f32_16x16x32_bf16 v[52:55], v[206:209], v[214:217], v[52:55]
	v_mfma_f32_16x16x32_bf16 v[40:43], v[198:201], v[222:225], v[40:43]
	v_mfma_f32_16x16x32_bf16 v[36:39], v[206:209], v[222:225], v[36:39]
	v_mfma_f32_16x16x32_bf16 v[24:27], v[198:201], v[230:233], v[24:27]
	v_mfma_f32_16x16x32_bf16 v[20:23], v[206:209], v[230:233], v[20:23]
	v_mfma_f32_16x16x32_bf16 v[8:11], v[198:201], v[238:241], v[8:11]
	v_mfma_f32_16x16x32_bf16 v[2:5], v[206:209], v[238:241], v[2:5]
	s_setprio 0
	s_barrier
	s_add_i32 s53, 0, 0x18000
	v_add_u32_e32 v1, s53, v158
	s_add_i32 s57, 0, 0x1c000
	ds_read_b128 v[174:177], v1
	ds_read_b128 v[178:181], v1 offset:1024
	ds_read_b128 v[182:185], v1 offset:2048
	ds_read_b128 v[190:193], v1 offset:3072
	v_add_u32_e32 v1, s57, v158
	ds_read_b128 v[194:197], v1
	ds_read_b128 v[198:201], v1 offset:1024
	ds_read_b128 v[202:205], v1 offset:2048
	ds_read_b128 v[206:209], v1 offset:3072
	s_add_u32 s62, s62, 0x40000
	s_addc_u32 s63, s63, 0
	s_mov_b32 m0, s40
	v_lshl_add_u64 v[6:7], s[62:63], 0, v[132:133]
	ds_read_b128 v[210:213], v169 offset:32768
	ds_read_b128 v[214:217], v169 offset:33792
	ds_read_b128 v[218:221], v169 offset:34816
	ds_read_b128 v[222:225], v169 offset:35840
	ds_read_b128 v[226:229], v169 offset:36864
	ds_read_b128 v[230:233], v169 offset:37888
	ds_read_b128 v[234:237], v169 offset:38912
	ds_read_b128 v[238:241], v169 offset:39936
	global_load_lds_dwordx4 v[6:7], off
	v_lshl_add_u64 v[6:7], s[62:63], 0, v[136:137]
	s_mov_b32 m0, s41
	s_nop 0
	global_load_lds_dwordx4 v[6:7], off
	s_waitcnt vmcnt(8)
	s_waitcnt lgkmcnt(0)
	v_mfma_f32_16x16x32_bf16 v[128:131], v[174:177], v[210:213], v[128:131]
	v_mfma_f32_16x16x32_bf16 v[124:127], v[182:185], v[210:213], v[124:127]
	v_mfma_f32_16x16x32_bf16 v[112:115], v[174:177], v[218:221], v[112:115]
	v_mfma_f32_16x16x32_bf16 v[108:111], v[182:185], v[218:221], v[108:111]
	v_mfma_f32_16x16x32_bf16 v[96:99], v[174:177], v[226:229], v[96:99]
	v_mfma_f32_16x16x32_bf16 v[92:95], v[182:185], v[226:229], v[92:95]
	v_mfma_f32_16x16x32_bf16 v[80:83], v[174:177], v[234:237], v[80:83]
	v_mfma_f32_16x16x32_bf16 v[76:79], v[182:185], v[234:237], v[76:79]
	s_barrier
	s_setprio 1
	v_mfma_f32_16x16x32_bf16 v[128:131], v[178:181], v[214:217], v[128:131]
	v_mfma_f32_16x16x32_bf16 v[124:127], v[190:193], v[214:217], v[124:127]
	v_mfma_f32_16x16x32_bf16 v[112:115], v[178:181], v[222:225], v[112:115]
	v_mfma_f32_16x16x32_bf16 v[108:111], v[190:193], v[222:225], v[108:111]
	v_mfma_f32_16x16x32_bf16 v[96:99], v[178:181], v[230:233], v[96:99]
	v_mfma_f32_16x16x32_bf16 v[92:95], v[190:193], v[230:233], v[92:95]
	v_mfma_f32_16x16x32_bf16 v[80:83], v[178:181], v[238:241], v[80:83]
	v_mfma_f32_16x16x32_bf16 v[76:79], v[190:193], v[238:241], v[76:79]
	s_setprio 0
	s_setprio 1
	v_mfma_f32_16x16x32_bf16 v[120:123], v[194:197], v[210:213], v[120:123]
	v_mfma_f32_16x16x32_bf16 v[116:119], v[202:205], v[210:213], v[116:119]
	v_mfma_f32_16x16x32_bf16 v[104:107], v[194:197], v[218:221], v[104:107]
	v_mfma_f32_16x16x32_bf16 v[100:103], v[202:205], v[218:221], v[100:103]
	v_mfma_f32_16x16x32_bf16 v[88:91], v[194:197], v[226:229], v[88:91]
	v_mfma_f32_16x16x32_bf16 v[84:87], v[202:205], v[226:229], v[84:87]
	v_mfma_f32_16x16x32_bf16 v[72:75], v[194:197], v[234:237], v[72:75]
	v_mfma_f32_16x16x32_bf16 v[68:71], v[202:205], v[234:237], v[68:71]
	v_mfma_f32_16x16x32_bf16 v[120:123], v[198:201], v[214:217], v[120:123]
	v_mfma_f32_16x16x32_bf16 v[116:119], v[206:209], v[214:217], v[116:119]
	v_mfma_f32_16x16x32_bf16 v[104:107], v[198:201], v[222:225], v[104:107]
	v_mfma_f32_16x16x32_bf16 v[100:103], v[206:209], v[222:225], v[100:103]
	v_mfma_f32_16x16x32_bf16 v[88:91], v[198:201], v[230:233], v[88:91]
	v_mfma_f32_16x16x32_bf16 v[84:87], v[206:209], v[230:233], v[84:87]
	v_mfma_f32_16x16x32_bf16 v[72:75], v[198:201], v[238:241], v[72:75]
	v_mfma_f32_16x16x32_bf16 v[68:71], v[206:209], v[238:241], v[68:71]
	s_setprio 0
	s_barrier
	s_add_i32 s53, s53, s33
	v_lshl_add_u64 v[6:7], v[186:187], 0, s[14:15]
	s_mov_b32 m0, s53
	ds_read_b128 v[210:213], v169 offset:49152
	ds_read_b128 v[214:217], v169 offset:50176
	ds_read_b128 v[218:221], v169 offset:51200
	ds_read_b128 v[222:225], v169 offset:52224
	ds_read_b128 v[226:229], v169 offset:53248
	ds_read_b128 v[230:233], v169 offset:54272
	ds_read_b128 v[234:237], v169 offset:55296
	ds_read_b128 v[238:241], v169 offset:56320
	global_load_lds_dwordx4 v[6:7], off
	s_add_i32 m0, s53, 0x2000
	s_add_u32 s60, s60, 0x40080
	v_lshl_add_u64 v[6:7], v[242:243], 0, s[14:15]
	s_addc_u32 s61, s61, 0
	s_add_i32 s53, s57, s33
	global_load_lds_dwordx4 v[6:7], off
	v_lshl_add_u64 v[6:7], s[60:61], 0, v[134:135]
	s_mov_b32 m0, s53
	s_nop 0
	global_load_lds_dwordx4 v[6:7], off
	v_lshl_add_u64 v[6:7], s[60:61], 0, v[138:139]
	s_add_i32 m0, s53, 0x2000
	s_nop 0
	global_load_lds_dwordx4 v[6:7], off
	v_lshl_add_u64 v[6:7], v[244:245], 0, s[14:15]
	s_mov_b32 m0, s42
	s_nop 0
	global_load_lds_dwordx4 v[6:7], off
	v_lshl_add_u64 v[6:7], v[246:247], 0, s[14:15]
	s_mov_b32 m0, s43
	s_nop 0
	global_load_lds_dwordx4 v[6:7], off
	s_waitcnt vmcnt(8)
	s_waitcnt lgkmcnt(0)
	v_mfma_f32_16x16x32_bf16 v[64:67], v[174:177], v[210:213], v[64:67]
	v_mfma_f32_16x16x32_bf16 v[60:63], v[182:185], v[210:213], v[60:63]
	v_mfma_f32_16x16x32_bf16 v[48:51], v[174:177], v[218:221], v[48:51]
	v_mfma_f32_16x16x32_bf16 v[44:47], v[182:185], v[218:221], v[44:47]
	v_mfma_f32_16x16x32_bf16 v[32:35], v[174:177], v[226:229], v[32:35]
	v_mfma_f32_16x16x32_bf16 v[28:31], v[182:185], v[226:229], v[28:31]
	v_mfma_f32_16x16x32_bf16 v[16:19], v[174:177], v[234:237], v[16:19]
	v_mfma_f32_16x16x32_bf16 v[12:15], v[182:185], v[234:237], v[12:15]
	s_barrier
	s_setprio 1
	v_mfma_f32_16x16x32_bf16 v[64:67], v[178:181], v[214:217], v[64:67]
	v_mfma_f32_16x16x32_bf16 v[60:63], v[190:193], v[214:217], v[60:63]
	v_mfma_f32_16x16x32_bf16 v[48:51], v[178:181], v[222:225], v[48:51]
	v_mfma_f32_16x16x32_bf16 v[44:47], v[190:193], v[222:225], v[44:47]
	v_mfma_f32_16x16x32_bf16 v[32:35], v[178:181], v[230:233], v[32:35]
	v_mfma_f32_16x16x32_bf16 v[28:31], v[190:193], v[230:233], v[28:31]
	v_mfma_f32_16x16x32_bf16 v[16:19], v[178:181], v[238:241], v[16:19]
	v_mfma_f32_16x16x32_bf16 v[12:15], v[190:193], v[238:241], v[12:15]
	s_setprio 0
	s_setprio 1
	v_mfma_f32_16x16x32_bf16 v[56:59], v[194:197], v[210:213], v[56:59]
	v_mfma_f32_16x16x32_bf16 v[52:55], v[202:205], v[210:213], v[52:55]
	v_mfma_f32_16x16x32_bf16 v[40:43], v[194:197], v[218:221], v[40:43]
	v_mfma_f32_16x16x32_bf16 v[36:39], v[202:205], v[218:221], v[36:39]
	v_mfma_f32_16x16x32_bf16 v[24:27], v[194:197], v[226:229], v[24:27]
	v_mfma_f32_16x16x32_bf16 v[20:23], v[202:205], v[226:229], v[20:23]
	v_mfma_f32_16x16x32_bf16 v[6:9], v[194:197], v[234:237], v[8:11]
	v_mfma_f32_16x16x32_bf16 v[2:5], v[202:205], v[234:237], v[2:5]
	v_mfma_f32_16x16x32_bf16 v[56:59], v[198:201], v[214:217], v[56:59]
	v_mfma_f32_16x16x32_bf16 v[52:55], v[206:209], v[214:217], v[52:55]
	v_mfma_f32_16x16x32_bf16 v[40:43], v[198:201], v[222:225], v[40:43]
	v_mfma_f32_16x16x32_bf16 v[36:39], v[206:209], v[222:225], v[36:39]
	v_mfma_f32_16x16x32_bf16 v[24:27], v[198:201], v[230:233], v[24:27]
	v_mfma_f32_16x16x32_bf16 v[20:23], v[206:209], v[230:233], v[20:23]
	v_mfma_f32_16x16x32_bf16 v[8:11], v[198:201], v[238:241], v[6:9]
	v_mfma_f32_16x16x32_bf16 v[4:7], v[206:209], v[238:241], v[2:5]
	s_setprio 0
	s_barrier
	s_add_i32 s52, s52, 2
	s_add_u32 s54, s54, 0x100
	s_addc_u32 s55, s55, 0
	s_cmp_gt_u32 s52, 13
	s_cbranch_scc1 .LBB0_633

.LBB0_980:
	ds_read_b128 v[144:147], v151
	ds_read_b128 v[156:159], v151 offset:1024
	ds_read_b128 v[160:163], v151 offset:2048
	ds_read_b128 v[164:167], v151 offset:3072
	ds_read_b128 v[168:171], v152
	ds_read_b128 v[172:175], v152 offset:1024
	ds_read_b128 v[176:179], v152 offset:2048
	ds_read_b128 v[180:183], v152 offset:3072
	s_add_u32 s34, s22, 0xfffc0080
	s_addc_u32 s35, s23, -1
	s_cmp_eq_u32 s55, 12
	s_cselect_b32 s37, s15, s35
	s_cselect_b32 s36, s51, s34
	s_cselect_b32 s35, s13, s54
	s_cselect_b32 s34, s52, s53
	v_lshl_add_u64 v[218:219], s[22:23], 0, v[136:137]
	s_add_i32 m0, s21, 0xc000
	ds_read_b128 v[184:187], v153
	ds_read_b128 v[190:193], v153 offset:1024
	ds_read_b128 v[194:197], v153 offset:2048
	ds_read_b128 v[198:201], v153 offset:3072
	ds_read_b128 v[202:205], v153 offset:4096
	ds_read_b128 v[206:209], v153 offset:5120
	ds_read_b128 v[210:213], v153 offset:6144
	ds_read_b128 v[214:217], v153 offset:7168
	global_load_lds_dwordx4 v[218:219], off
	v_lshl_add_u64 v[218:219], s[22:23], 0, v[138:139]
	s_add_i32 m0, s21, 0xe000
	s_nop 0
	global_load_lds_dwordx4 v[218:219], off
	s_waitcnt vmcnt(8)
	s_waitcnt lgkmcnt(0)
	v_mfma_f32_16x16x32_bf16 v[116:119], v[144:147], v[184:187], v[116:119]
	v_mfma_f32_16x16x32_bf16 v[112:115], v[160:163], v[184:187], v[112:115]
	v_mfma_f32_16x16x32_bf16 v[104:107], v[144:147], v[194:197], v[104:107]
	v_mfma_f32_16x16x32_bf16 v[96:99], v[160:163], v[194:197], v[96:99]
	v_mfma_f32_16x16x32_bf16 v[88:91], v[144:147], v[202:205], v[88:91]
	v_mfma_f32_16x16x32_bf16 v[80:83], v[160:163], v[202:205], v[80:83]
	v_mfma_f32_16x16x32_bf16 v[72:75], v[144:147], v[210:213], v[72:75]
	v_mfma_f32_16x16x32_bf16 v[68:71], v[160:163], v[210:213], v[68:71]
	s_barrier
	s_setprio 1
	v_mfma_f32_16x16x32_bf16 v[116:119], v[156:159], v[190:193], v[116:119]
	v_mfma_f32_16x16x32_bf16 v[112:115], v[164:167], v[190:193], v[112:115]
	v_mfma_f32_16x16x32_bf16 v[104:107], v[156:159], v[198:201], v[104:107]
	v_mfma_f32_16x16x32_bf16 v[96:99], v[164:167], v[198:201], v[96:99]
	v_mfma_f32_16x16x32_bf16 v[88:91], v[156:159], v[206:209], v[88:91]
	v_mfma_f32_16x16x32_bf16 v[80:83], v[164:167], v[206:209], v[80:83]
	v_mfma_f32_16x16x32_bf16 v[72:75], v[156:159], v[214:217], v[72:75]
	v_mfma_f32_16x16x32_bf16 v[68:71], v[164:167], v[214:217], v[68:71]
	s_setprio 0
	s_setprio 1
	v_mfma_f32_16x16x32_bf16 v[124:127], v[168:171], v[184:187], v[124:127]
	v_mfma_f32_16x16x32_bf16 v[120:123], v[176:179], v[184:187], v[120:123]
	v_mfma_f32_16x16x32_bf16 v[108:111], v[168:171], v[194:197], v[108:111]
	v_mfma_f32_16x16x32_bf16 v[100:103], v[176:179], v[194:197], v[100:103]
	v_mfma_f32_16x16x32_bf16 v[92:95], v[168:171], v[202:205], v[92:95]
	v_mfma_f32_16x16x32_bf16 v[84:87], v[176:179], v[202:205], v[84:87]
	v_mfma_f32_16x16x32_bf16 v[76:79], v[168:171], v[210:213], v[76:79]
	v_mfma_f32_16x16x32_bf16 v[64:67], v[176:179], v[210:213], v[64:67]
	v_mfma_f32_16x16x32_bf16 v[124:127], v[172:175], v[190:193], v[124:127]
	v_mfma_f32_16x16x32_bf16 v[120:123], v[180:183], v[190:193], v[120:123]
	v_mfma_f32_16x16x32_bf16 v[108:111], v[172:175], v[198:201], v[108:111]
	v_mfma_f32_16x16x32_bf16 v[100:103], v[180:183], v[198:201], v[100:103]
	v_mfma_f32_16x16x32_bf16 v[92:95], v[172:175], v[206:209], v[92:95]
	v_mfma_f32_16x16x32_bf16 v[84:87], v[180:183], v[206:209], v[84:87]
	v_mfma_f32_16x16x32_bf16 v[76:79], v[172:175], v[214:217], v[76:79]
	v_mfma_f32_16x16x32_bf16 v[64:67], v[180:183], v[214:217], v[64:67]
	s_setprio 0
	s_barrier
	s_add_i32 s56, s47, s38
	v_lshl_add_u64 v[218:219], s[34:35], 0, v[130:131]
	s_mov_b32 m0, s56
	ds_read_b128 v[184:187], v153 offset:16384
	ds_read_b128 v[190:193], v153 offset:17408
	ds_read_b128 v[194:197], v153 offset:18432
	ds_read_b128 v[198:201], v153 offset:19456
	ds_read_b128 v[202:205], v153 offset:20480
	ds_read_b128 v[206:209], v153 offset:21504
	ds_read_b128 v[210:213], v153 offset:22528
	ds_read_b128 v[214:217], v153 offset:23552
	global_load_lds_dwordx4 v[218:219], off
	s_add_i32 m0, s56, 0x2000
	s_add_u32 s56, s34, 0x40000
	v_lshl_add_u64 v[220:221], s[34:35], 0, v[134:135]
	s_addc_u32 s57, s35, 0
	s_add_i32 s58, s48, s38
	global_load_lds_dwordx4 v[220:221], off
	v_lshl_add_u64 v[222:223], s[56:57], 0, v[130:131]
	s_mov_b32 m0, s58
	v_lshl_add_u64 v[224:225], s[36:37], 0, v[132:133]
	global_load_lds_dwordx4 v[222:223], off
	v_lshl_add_u64 v[222:223], s[56:57], 0, v[134:135]
	s_add_i32 m0, s58, 0x2000
	s_nop 0
	global_load_lds_dwordx4 v[222:223], off
	v_lshl_add_u64 v[222:223], s[36:37], 0, v[128:129]
	s_mov_b32 m0, s21
	s_nop 0
	global_load_lds_dwordx4 v[222:223], off
	s_mov_b32 m0, s39
	s_nop 0
	global_load_lds_dwordx4 v[224:225], off
	s_waitcnt vmcnt(8)
	s_waitcnt lgkmcnt(0)
	v_mfma_f32_16x16x32_bf16 v[56:59], v[144:147], v[184:187], v[56:59]
	v_mfma_f32_16x16x32_bf16 v[48:51], v[160:163], v[184:187], v[48:51]
	v_mfma_f32_16x16x32_bf16 v[40:43], v[144:147], v[194:197], v[40:43]
	v_mfma_f32_16x16x32_bf16 v[32:35], v[160:163], v[194:197], v[32:35]
	v_mfma_f32_16x16x32_bf16 v[24:27], v[144:147], v[202:205], v[24:27]
	v_mfma_f32_16x16x32_bf16 v[16:19], v[160:163], v[202:205], v[16:19]
	v_mfma_f32_16x16x32_bf16 v[8:11], v[144:147], v[210:213], v[8:11]
	v_mfma_f32_16x16x32_bf16 v[0:3], v[160:163], v[210:213], v[0:3]
	s_barrier
	s_setprio 1
	v_mfma_f32_16x16x32_bf16 v[56:59], v[156:159], v[190:193], v[56:59]
	v_mfma_f32_16x16x32_bf16 v[48:51], v[164:167], v[190:193], v[48:51]
	v_mfma_f32_16x16x32_bf16 v[40:43], v[156:159], v[198:201], v[40:43]
	v_mfma_f32_16x16x32_bf16 v[32:35], v[164:167], v[198:201], v[32:35]
	v_mfma_f32_16x16x32_bf16 v[24:27], v[156:159], v[206:209], v[24:27]
	v_mfma_f32_16x16x32_bf16 v[16:19], v[164:167], v[206:209], v[16:19]
	v_mfma_f32_16x16x32_bf16 v[8:11], v[156:159], v[214:217], v[8:11]
	v_mfma_f32_16x16x32_bf16 v[0:3], v[164:167], v[214:217], v[0:3]
	s_setprio 0
	s_setprio 1
	v_mfma_f32_16x16x32_bf16 v[60:63], v[168:171], v[184:187], v[60:63]
	v_mfma_f32_16x16x32_bf16 v[52:55], v[176:179], v[184:187], v[52:55]
	v_mfma_f32_16x16x32_bf16 v[44:47], v[168:171], v[194:197], v[44:47]
	v_mfma_f32_16x16x32_bf16 v[36:39], v[176:179], v[194:197], v[36:39]
	v_mfma_f32_16x16x32_bf16 v[28:31], v[168:171], v[202:205], v[28:31]
	v_mfma_f32_16x16x32_bf16 v[20:23], v[176:179], v[202:205], v[20:23]
	v_mfma_f32_16x16x32_bf16 v[12:15], v[168:171], v[210:213], v[12:15]
	v_mfma_f32_16x16x32_bf16 v[4:7], v[176:179], v[210:213], v[4:7]
	v_mfma_f32_16x16x32_bf16 v[60:63], v[172:175], v[190:193], v[60:63]
	v_mfma_f32_16x16x32_bf16 v[52:55], v[180:183], v[190:193], v[52:55]
	v_mfma_f32_16x16x32_bf16 v[44:47], v[172:175], v[198:201], v[44:47]
	v_mfma_f32_16x16x32_bf16 v[36:39], v[180:183], v[198:201], v[36:39]
	v_mfma_f32_16x16x32_bf16 v[28:31], v[172:175], v[206:209], v[28:31]
	v_mfma_f32_16x16x32_bf16 v[20:23], v[180:183], v[206:209], v[20:23]
	v_mfma_f32_16x16x32_bf16 v[12:15], v[172:175], v[214:217], v[12:15]
	v_mfma_f32_16x16x32_bf16 v[4:7], v[180:183], v[214:217], v[4:7]
	s_setprio 0
	s_barrier
	s_add_i32 s56, 0, 0x18000
	v_add_u32_e32 v155, s56, v149
	s_add_i32 s57, 0, 0x1c000
	ds_read_b128 v[144:147], v155
	ds_read_b128 v[156:159], v155 offset:1024
	ds_read_b128 v[160:163], v155 offset:2048
	ds_read_b128 v[164:167], v155 offset:3072
	v_add_u32_e32 v155, s57, v149
	ds_read_b128 v[168:171], v155
	ds_read_b128 v[172:175], v155 offset:1024
	ds_read_b128 v[176:179], v155 offset:2048
	ds_read_b128 v[180:183], v155 offset:3072
	s_add_u32 s36, s36, 0x40000
	s_addc_u32 s37, s37, 0
	s_mov_b32 m0, s40
	v_lshl_add_u64 v[226:227], s[36:37], 0, v[128:129]
	ds_read_b128 v[184:187], v153 offset:32768
	ds_read_b128 v[190:193], v153 offset:33792
	ds_read_b128 v[194:197], v153 offset:34816
	ds_read_b128 v[198:201], v153 offset:35840
	ds_read_b128 v[202:205], v153 offset:36864
	ds_read_b128 v[206:209], v153 offset:37888
	ds_read_b128 v[210:213], v153 offset:38912
	ds_read_b128 v[214:217], v153 offset:39936
	global_load_lds_dwordx4 v[226:227], off
	v_lshl_add_u64 v[226:227], s[36:37], 0, v[132:133]
	s_mov_b32 m0, s41
	s_nop 0
	global_load_lds_dwordx4 v[226:227], off
	s_waitcnt vmcnt(8)
	s_waitcnt lgkmcnt(0)
	v_mfma_f32_16x16x32_bf16 v[116:119], v[144:147], v[184:187], v[116:119]
	v_mfma_f32_16x16x32_bf16 v[112:115], v[160:163], v[184:187], v[112:115]
	v_mfma_f32_16x16x32_bf16 v[104:107], v[144:147], v[194:197], v[104:107]
	v_mfma_f32_16x16x32_bf16 v[96:99], v[160:163], v[194:197], v[96:99]
	v_mfma_f32_16x16x32_bf16 v[88:91], v[144:147], v[202:205], v[88:91]
	v_mfma_f32_16x16x32_bf16 v[80:83], v[160:163], v[202:205], v[80:83]
	v_mfma_f32_16x16x32_bf16 v[72:75], v[144:147], v[210:213], v[72:75]
	v_mfma_f32_16x16x32_bf16 v[68:71], v[160:163], v[210:213], v[68:71]
	s_barrier
	s_setprio 1
	v_mfma_f32_16x16x32_bf16 v[116:119], v[156:159], v[190:193], v[116:119]
	v_mfma_f32_16x16x32_bf16 v[112:115], v[164:167], v[190:193], v[112:115]
	v_mfma_f32_16x16x32_bf16 v[104:107], v[156:159], v[198:201], v[104:107]
	v_mfma_f32_16x16x32_bf16 v[96:99], v[164:167], v[198:201], v[96:99]
	v_mfma_f32_16x16x32_bf16 v[88:91], v[156:159], v[206:209], v[88:91]
	v_mfma_f32_16x16x32_bf16 v[80:83], v[164:167], v[206:209], v[80:83]
	v_mfma_f32_16x16x32_bf16 v[72:75], v[156:159], v[214:217], v[72:75]
	v_mfma_f32_16x16x32_bf16 v[68:71], v[164:167], v[214:217], v[68:71]
	s_setprio 0
	s_setprio 1
	v_mfma_f32_16x16x32_bf16 v[124:127], v[168:171], v[184:187], v[124:127]
	v_mfma_f32_16x16x32_bf16 v[120:123], v[176:179], v[184:187], v[120:123]
	v_mfma_f32_16x16x32_bf16 v[108:111], v[168:171], v[194:197], v[108:111]
	v_mfma_f32_16x16x32_bf16 v[100:103], v[176:179], v[194:197], v[100:103]
	v_mfma_f32_16x16x32_bf16 v[92:95], v[168:171], v[202:205], v[92:95]
	v_mfma_f32_16x16x32_bf16 v[84:87], v[176:179], v[202:205], v[84:87]
	v_mfma_f32_16x16x32_bf16 v[76:79], v[168:171], v[210:213], v[76:79]
	v_mfma_f32_16x16x32_bf16 v[64:67], v[176:179], v[210:213], v[64:67]
	v_mfma_f32_16x16x32_bf16 v[124:127], v[172:175], v[190:193], v[124:127]
	v_mfma_f32_16x16x32_bf16 v[120:123], v[180:183], v[190:193], v[120:123]
	v_mfma_f32_16x16x32_bf16 v[108:111], v[172:175], v[198:201], v[108:111]
	v_mfma_f32_16x16x32_bf16 v[100:103], v[180:183], v[198:201], v[100:103]
	v_mfma_f32_16x16x32_bf16 v[92:95], v[172:175], v[206:209], v[92:95]
	v_mfma_f32_16x16x32_bf16 v[84:87], v[180:183], v[206:209], v[84:87]
	v_mfma_f32_16x16x32_bf16 v[76:79], v[172:175], v[214:217], v[76:79]
	v_mfma_f32_16x16x32_bf16 v[64:67], v[180:183], v[214:217], v[64:67]
	s_setprio 0
	s_barrier
	s_add_i32 s36, s56, s38
	v_lshl_add_u64 v[218:219], v[218:219], 0, s[8:9]
	s_mov_b32 m0, s36
	ds_read_b128 v[184:187], v153 offset:49152
	ds_read_b128 v[190:193], v153 offset:50176
	ds_read_b128 v[194:197], v153 offset:51200
	ds_read_b128 v[198:201], v153 offset:52224
	ds_read_b128 v[202:205], v153 offset:53248
	ds_read_b128 v[206:209], v153 offset:54272
	ds_read_b128 v[210:213], v153 offset:55296
	ds_read_b128 v[214:217], v153 offset:56320
	global_load_lds_dwordx4 v[218:219], off
	s_add_i32 m0, s36, 0x2000
	s_add_u32 s34, s34, 0x40080
	v_lshl_add_u64 v[218:219], v[220:221], 0, s[8:9]
	s_addc_u32 s35, s35, 0
	s_add_i32 s36, s57, s38
	global_load_lds_dwordx4 v[218:219], off
	v_lshl_add_u64 v[218:219], s[34:35], 0, v[130:131]
	s_mov_b32 m0, s36
	s_nop 0
	global_load_lds_dwordx4 v[218:219], off
	v_lshl_add_u64 v[218:219], s[34:35], 0, v[134:135]
	s_add_i32 m0, s36, 0x2000
	s_nop 0
	global_load_lds_dwordx4 v[218:219], off
	v_lshl_add_u64 v[218:219], v[222:223], 0, s[8:9]
	s_mov_b32 m0, s43
	s_nop 0
	global_load_lds_dwordx4 v[218:219], off
	v_lshl_add_u64 v[218:219], v[224:225], 0, s[8:9]
	s_mov_b32 m0, s44
	s_nop 0
	global_load_lds_dwordx4 v[218:219], off
	s_waitcnt vmcnt(8)
	s_waitcnt lgkmcnt(0)
	v_mfma_f32_16x16x32_bf16 v[56:59], v[144:147], v[184:187], v[56:59]
	v_mfma_f32_16x16x32_bf16 v[48:51], v[160:163], v[184:187], v[48:51]
	v_mfma_f32_16x16x32_bf16 v[40:43], v[144:147], v[194:197], v[40:43]
	v_mfma_f32_16x16x32_bf16 v[32:35], v[160:163], v[194:197], v[32:35]
	v_mfma_f32_16x16x32_bf16 v[24:27], v[144:147], v[202:205], v[24:27]
	v_mfma_f32_16x16x32_bf16 v[16:19], v[160:163], v[202:205], v[16:19]
	v_mfma_f32_16x16x32_bf16 v[8:11], v[144:147], v[210:213], v[8:11]
	v_mfma_f32_16x16x32_bf16 v[0:3], v[160:163], v[210:213], v[0:3]
	s_barrier
	s_setprio 1
	v_mfma_f32_16x16x32_bf16 v[56:59], v[156:159], v[190:193], v[56:59]
	v_mfma_f32_16x16x32_bf16 v[48:51], v[164:167], v[190:193], v[48:51]
	v_mfma_f32_16x16x32_bf16 v[40:43], v[156:159], v[198:201], v[40:43]
	v_mfma_f32_16x16x32_bf16 v[32:35], v[164:167], v[198:201], v[32:35]
	v_mfma_f32_16x16x32_bf16 v[24:27], v[156:159], v[206:209], v[24:27]
	v_mfma_f32_16x16x32_bf16 v[16:19], v[164:167], v[206:209], v[16:19]
	v_mfma_f32_16x16x32_bf16 v[8:11], v[156:159], v[214:217], v[8:11]
	v_mfma_f32_16x16x32_bf16 v[0:3], v[164:167], v[214:217], v[0:3]
	s_setprio 0
	s_setprio 1
	v_mfma_f32_16x16x32_bf16 v[60:63], v[168:171], v[184:187], v[60:63]
	v_mfma_f32_16x16x32_bf16 v[52:55], v[176:179], v[184:187], v[52:55]
	v_mfma_f32_16x16x32_bf16 v[44:47], v[168:171], v[194:197], v[44:47]
	v_mfma_f32_16x16x32_bf16 v[36:39], v[176:179], v[194:197], v[36:39]
	v_mfma_f32_16x16x32_bf16 v[28:31], v[168:171], v[202:205], v[28:31]
	v_mfma_f32_16x16x32_bf16 v[20:23], v[176:179], v[202:205], v[20:23]
	v_mfma_f32_16x16x32_bf16 v[12:15], v[168:171], v[210:213], v[12:15]
	v_mfma_f32_16x16x32_bf16 v[4:7], v[176:179], v[210:213], v[4:7]
	v_mfma_f32_16x16x32_bf16 v[60:63], v[172:175], v[190:193], v[60:63]
	v_mfma_f32_16x16x32_bf16 v[52:55], v[180:183], v[190:193], v[52:55]
	v_mfma_f32_16x16x32_bf16 v[44:47], v[172:175], v[198:201], v[44:47]
	v_mfma_f32_16x16x32_bf16 v[36:39], v[180:183], v[198:201], v[36:39]
	v_mfma_f32_16x16x32_bf16 v[28:31], v[172:175], v[206:209], v[28:31]
	v_mfma_f32_16x16x32_bf16 v[20:23], v[180:183], v[206:209], v[20:23]
	v_mfma_f32_16x16x32_bf16 v[12:15], v[172:175], v[214:217], v[12:15]
	v_mfma_f32_16x16x32_bf16 v[4:7], v[180:183], v[214:217], v[4:7]
	s_setprio 0
	s_barrier
	s_add_i32 s55, s55, 2
	s_add_u32 s22, s22, 0x100
	s_addc_u32 s23, s23, 0
	s_add_u32 s53, s53, 0x100
	s_addc_u32 s54, s54, 0
	s_cmp_gt_u32 s55, 13
	s_cbranch_scc0 .LBB0_980
	v_lshl_add_u32 v236, s20, 8, v148
	v_lshlrev_b32_e32 v236, 2, v236
	global_load_dword v228, v236, s[6:7]
	global_load_dword v229, v236, s[6:7] offset:64
	global_load_dword v230, v236, s[6:7] offset:128
	global_load_dword v231, v236, s[6:7] offset:192
	global_load_dword v232, v236, s[6:7] offset:512
	global_load_dword v233, v236, s[6:7] offset:576
	global_load_dword v234, v236, s[6:7] offset:640
	global_load_dword v235, v236, s[6:7] offset:704
	s_and_b64 vcc, exec, s[10:11]
	s_cbranch_vccz .LBB0_983
	s_barrier

.LBB0_1061:
	ds_read_b128 v[144:147], v187
	ds_read_b128 v[148:151], v187 offset:1024
	ds_read_b128 v[152:155], v187 offset:2048
	ds_read_b128 v[156:159], v187 offset:3072
	ds_read_b128 v[160:163], v189
	ds_read_b128 v[164:167], v189 offset:1024
	ds_read_b128 v[168:171], v189 offset:2048
	ds_read_b128 v[172:175], v189 offset:3072
	s_add_u32 s34, s4, 0xfff50080
	s_addc_u32 s35, s5, -1
	s_cmp_eq_u32 s58, 40
	s_cselect_b32 s37, s19, s35
	s_cselect_b32 s36, s18, s34
	s_cselect_b32 s35, s21, s27
	s_cselect_b32 s34, s20, s23
	v_lshl_add_u64 v[176:177], s[4:5], 0, v[136:137]
	s_add_i32 m0, s40, 0xc000
	ds_read_b128 v[192:195], v190
	ds_read_b128 v[196:199], v190 offset:1024
	ds_read_b128 v[200:203], v190 offset:2048
	ds_read_b128 v[204:207], v190 offset:3072
	ds_read_b128 v[208:211], v190 offset:4096
	ds_read_b128 v[212:215], v190 offset:5120
	ds_read_b128 v[216:219], v190 offset:6144
	ds_read_b128 v[220:223], v190 offset:7168
	global_load_lds_dwordx4 v[176:177], off
	v_lshl_add_u64 v[176:177], s[4:5], 0, v[138:139]
	s_add_i32 m0, s40, 0xe000
	s_nop 0
	global_load_lds_dwordx4 v[176:177], off
	s_waitcnt vmcnt(8)
	s_waitcnt lgkmcnt(0)
	v_mfma_f32_16x16x32_bf16 v[124:127], v[144:147], v[192:195], v[124:127]
	v_mfma_f32_16x16x32_bf16 v[120:123], v[152:155], v[192:195], v[120:123]
	v_mfma_f32_16x16x32_bf16 v[108:111], v[144:147], v[200:203], v[108:111]
	v_mfma_f32_16x16x32_bf16 v[104:107], v[152:155], v[200:203], v[104:107]
	v_mfma_f32_16x16x32_bf16 v[92:95], v[144:147], v[208:211], v[92:95]
	v_mfma_f32_16x16x32_bf16 v[88:91], v[152:155], v[208:211], v[88:91]
	v_mfma_f32_16x16x32_bf16 v[76:79], v[144:147], v[216:219], v[76:79]
	v_mfma_f32_16x16x32_bf16 v[72:75], v[152:155], v[216:219], v[72:75]
	s_barrier
	s_setprio 1
	v_mfma_f32_16x16x32_bf16 v[124:127], v[148:151], v[196:199], v[124:127]
	v_mfma_f32_16x16x32_bf16 v[120:123], v[156:159], v[196:199], v[120:123]
	v_mfma_f32_16x16x32_bf16 v[108:111], v[148:151], v[204:207], v[108:111]
	v_mfma_f32_16x16x32_bf16 v[104:107], v[156:159], v[204:207], v[104:107]
	v_mfma_f32_16x16x32_bf16 v[92:95], v[148:151], v[212:215], v[92:95]
	v_mfma_f32_16x16x32_bf16 v[88:91], v[156:159], v[212:215], v[88:91]
	v_mfma_f32_16x16x32_bf16 v[76:79], v[148:151], v[220:223], v[76:79]
	v_mfma_f32_16x16x32_bf16 v[72:75], v[156:159], v[220:223], v[72:75]
	s_setprio 0
	s_setprio 1
	v_mfma_f32_16x16x32_bf16 v[116:119], v[160:163], v[192:195], v[116:119]
	v_mfma_f32_16x16x32_bf16 v[112:115], v[168:171], v[192:195], v[112:115]
	v_mfma_f32_16x16x32_bf16 v[100:103], v[160:163], v[200:203], v[100:103]
	v_mfma_f32_16x16x32_bf16 v[96:99], v[168:171], v[200:203], v[96:99]
	v_mfma_f32_16x16x32_bf16 v[84:87], v[160:163], v[208:211], v[84:87]
	v_mfma_f32_16x16x32_bf16 v[80:83], v[168:171], v[208:211], v[80:83]
	v_mfma_f32_16x16x32_bf16 v[68:71], v[160:163], v[216:219], v[68:71]
	v_mfma_f32_16x16x32_bf16 v[64:67], v[168:171], v[216:219], v[64:67]
	v_mfma_f32_16x16x32_bf16 v[116:119], v[164:167], v[196:199], v[116:119]
	v_mfma_f32_16x16x32_bf16 v[112:115], v[172:175], v[196:199], v[112:115]
	v_mfma_f32_16x16x32_bf16 v[100:103], v[164:167], v[204:207], v[100:103]
	v_mfma_f32_16x16x32_bf16 v[96:99], v[172:175], v[204:207], v[96:99]
	v_mfma_f32_16x16x32_bf16 v[84:87], v[164:167], v[212:215], v[84:87]
	v_mfma_f32_16x16x32_bf16 v[80:83], v[172:175], v[212:215], v[80:83]
	v_mfma_f32_16x16x32_bf16 v[68:71], v[164:167], v[220:223], v[68:71]
	v_mfma_f32_16x16x32_bf16 v[64:67], v[172:175], v[220:223], v[64:67]
	s_setprio 0
	s_barrier
	s_add_i32 s59, s54, s39
	v_lshl_add_u64 v[176:177], s[34:35], 0, v[130:131]
	s_mov_b32 m0, s59
	ds_read_b128 v[192:195], v190 offset:16384
	ds_read_b128 v[196:199], v190 offset:17408
	ds_read_b128 v[200:203], v190 offset:18432
	ds_read_b128 v[204:207], v190 offset:19456
	ds_read_b128 v[208:211], v190 offset:20480
	ds_read_b128 v[212:215], v190 offset:21504
	ds_read_b128 v[216:219], v190 offset:22528
	ds_read_b128 v[220:223], v190 offset:23552
	global_load_lds_dwordx4 v[176:177], off
	s_add_i32 m0, s59, 0x2000
	s_add_u32 s60, s34, 0xb0000
	v_lshl_add_u64 v[224:225], s[34:35], 0, v[134:135]
	s_addc_u32 s61, s35, 0
	s_add_i32 s59, s55, s39
	global_load_lds_dwordx4 v[224:225], off
	v_lshl_add_u64 v[226:227], s[60:61], 0, v[130:131]
	s_mov_b32 m0, s59
	v_lshl_add_u64 v[228:229], s[36:37], 0, v[132:133]
	global_load_lds_dwordx4 v[226:227], off
	v_lshl_add_u64 v[226:227], s[60:61], 0, v[134:135]
	s_add_i32 m0, s59, 0x2000
	s_nop 0
	global_load_lds_dwordx4 v[226:227], off
	v_lshl_add_u64 v[226:227], s[36:37], 0, v[128:129]
	s_mov_b32 m0, s40
	s_nop 0
	global_load_lds_dwordx4 v[226:227], off
	s_mov_b32 m0, s41
	s_nop 0
	global_load_lds_dwordx4 v[228:229], off
	s_waitcnt vmcnt(8)
	s_waitcnt lgkmcnt(0)
	v_mfma_f32_16x16x32_bf16 v[60:63], v[144:147], v[192:195], v[60:63]
	v_mfma_f32_16x16x32_bf16 v[56:59], v[152:155], v[192:195], v[56:59]
	v_mfma_f32_16x16x32_bf16 v[44:47], v[144:147], v[200:203], v[44:47]
	v_mfma_f32_16x16x32_bf16 v[40:43], v[152:155], v[200:203], v[40:43]
	v_mfma_f32_16x16x32_bf16 v[28:31], v[144:147], v[208:211], v[28:31]
	v_mfma_f32_16x16x32_bf16 v[24:27], v[152:155], v[208:211], v[24:27]
	v_mfma_f32_16x16x32_bf16 v[12:15], v[144:147], v[216:219], v[12:15]
	v_mfma_f32_16x16x32_bf16 v[8:11], v[152:155], v[216:219], v[8:11]
	s_barrier
	s_setprio 1
	v_mfma_f32_16x16x32_bf16 v[60:63], v[148:151], v[196:199], v[60:63]
	v_mfma_f32_16x16x32_bf16 v[56:59], v[156:159], v[196:199], v[56:59]
	v_mfma_f32_16x16x32_bf16 v[44:47], v[148:151], v[204:207], v[44:47]
	v_mfma_f32_16x16x32_bf16 v[40:43], v[156:159], v[204:207], v[40:43]
	v_mfma_f32_16x16x32_bf16 v[28:31], v[148:151], v[212:215], v[28:31]
	v_mfma_f32_16x16x32_bf16 v[24:27], v[156:159], v[212:215], v[24:27]
	v_mfma_f32_16x16x32_bf16 v[12:15], v[148:151], v[220:223], v[12:15]
	v_mfma_f32_16x16x32_bf16 v[8:11], v[156:159], v[220:223], v[8:11]
	s_setprio 0
	s_setprio 1
	v_mfma_f32_16x16x32_bf16 v[52:55], v[160:163], v[192:195], v[52:55]
	v_mfma_f32_16x16x32_bf16 v[48:51], v[168:171], v[192:195], v[48:51]
	v_mfma_f32_16x16x32_bf16 v[36:39], v[160:163], v[200:203], v[36:39]
	v_mfma_f32_16x16x32_bf16 v[32:35], v[168:171], v[200:203], v[32:35]
	v_mfma_f32_16x16x32_bf16 v[20:23], v[160:163], v[208:211], v[20:23]
	v_mfma_f32_16x16x32_bf16 v[16:19], v[168:171], v[208:211], v[16:19]
	v_mfma_f32_16x16x32_bf16 v[4:7], v[160:163], v[216:219], v[4:7]
	v_mfma_f32_16x16x32_bf16 v[0:3], v[168:171], v[216:219], v[0:3]
	v_mfma_f32_16x16x32_bf16 v[52:55], v[164:167], v[196:199], v[52:55]
	v_mfma_f32_16x16x32_bf16 v[48:51], v[172:175], v[196:199], v[48:51]
	v_mfma_f32_16x16x32_bf16 v[36:39], v[164:167], v[204:207], v[36:39]
	v_mfma_f32_16x16x32_bf16 v[32:35], v[172:175], v[204:207], v[32:35]
	v_mfma_f32_16x16x32_bf16 v[20:23], v[164:167], v[212:215], v[20:23]
	v_mfma_f32_16x16x32_bf16 v[16:19], v[172:175], v[212:215], v[16:19]
	v_mfma_f32_16x16x32_bf16 v[4:7], v[164:167], v[220:223], v[4:7]
	v_mfma_f32_16x16x32_bf16 v[0:3], v[172:175], v[220:223], v[0:3]
	s_setprio 0
	s_barrier
	s_add_i32 s59, 0, 0x18000
	s_add_i32 s60, 0, 0x1c000
	v_add_u32_e32 v156, s59, v183
	v_add_u32_e32 v172, s60, v183
	ds_read_b128 v[144:147], v156
	ds_read_b128 v[148:151], v156 offset:1024
	ds_read_b128 v[152:155], v156 offset:2048
	ds_read_b128 v[156:159], v156 offset:3072
	ds_read_b128 v[160:163], v172
	ds_read_b128 v[164:167], v172 offset:1024
	ds_read_b128 v[168:171], v172 offset:2048
	ds_read_b128 v[172:175], v172 offset:3072
	s_add_u32 s36, s36, 0xb0000
	s_addc_u32 s37, s37, 0
	s_mov_b32 m0, s42
	v_lshl_add_u64 v[230:231], s[36:37], 0, v[128:129]
	ds_read_b128 v[192:195], v190 offset:32768
	ds_read_b128 v[196:199], v190 offset:33792
	ds_read_b128 v[200:203], v190 offset:34816
	ds_read_b128 v[204:207], v190 offset:35840
	ds_read_b128 v[208:211], v190 offset:36864
	ds_read_b128 v[212:215], v190 offset:37888
	ds_read_b128 v[216:219], v190 offset:38912
	ds_read_b128 v[220:223], v190 offset:39936
	global_load_lds_dwordx4 v[230:231], off
	v_lshl_add_u64 v[230:231], s[36:37], 0, v[132:133]
	s_mov_b32 m0, s43
	s_nop 0
	global_load_lds_dwordx4 v[230:231], off
	s_waitcnt vmcnt(8)
	s_waitcnt lgkmcnt(0)
	v_mfma_f32_16x16x32_bf16 v[124:127], v[144:147], v[192:195], v[124:127]
	v_mfma_f32_16x16x32_bf16 v[120:123], v[152:155], v[192:195], v[120:123]
	v_mfma_f32_16x16x32_bf16 v[108:111], v[144:147], v[200:203], v[108:111]
	v_mfma_f32_16x16x32_bf16 v[104:107], v[152:155], v[200:203], v[104:107]
	v_mfma_f32_16x16x32_bf16 v[92:95], v[144:147], v[208:211], v[92:95]
	v_mfma_f32_16x16x32_bf16 v[88:91], v[152:155], v[208:211], v[88:91]
	v_mfma_f32_16x16x32_bf16 v[76:79], v[144:147], v[216:219], v[76:79]
	v_mfma_f32_16x16x32_bf16 v[72:75], v[152:155], v[216:219], v[72:75]
	s_barrier
	s_setprio 1
	v_mfma_f32_16x16x32_bf16 v[124:127], v[148:151], v[196:199], v[124:127]
	v_mfma_f32_16x16x32_bf16 v[120:123], v[156:159], v[196:199], v[120:123]
	v_mfma_f32_16x16x32_bf16 v[108:111], v[148:151], v[204:207], v[108:111]
	v_mfma_f32_16x16x32_bf16 v[104:107], v[156:159], v[204:207], v[104:107]
	v_mfma_f32_16x16x32_bf16 v[92:95], v[148:151], v[212:215], v[92:95]
	v_mfma_f32_16x16x32_bf16 v[88:91], v[156:159], v[212:215], v[88:91]
	v_mfma_f32_16x16x32_bf16 v[76:79], v[148:151], v[220:223], v[76:79]
	v_mfma_f32_16x16x32_bf16 v[72:75], v[156:159], v[220:223], v[72:75]
	s_setprio 0
	s_setprio 1
	v_mfma_f32_16x16x32_bf16 v[116:119], v[160:163], v[192:195], v[116:119]
	v_mfma_f32_16x16x32_bf16 v[112:115], v[168:171], v[192:195], v[112:115]
	v_mfma_f32_16x16x32_bf16 v[100:103], v[160:163], v[200:203], v[100:103]
	v_mfma_f32_16x16x32_bf16 v[96:99], v[168:171], v[200:203], v[96:99]
	v_mfma_f32_16x16x32_bf16 v[84:87], v[160:163], v[208:211], v[84:87]
	v_mfma_f32_16x16x32_bf16 v[80:83], v[168:171], v[208:211], v[80:83]
	v_mfma_f32_16x16x32_bf16 v[68:71], v[160:163], v[216:219], v[68:71]
	v_mfma_f32_16x16x32_bf16 v[64:67], v[168:171], v[216:219], v[64:67]
	v_mfma_f32_16x16x32_bf16 v[116:119], v[164:167], v[196:199], v[116:119]
	v_mfma_f32_16x16x32_bf16 v[112:115], v[172:175], v[196:199], v[112:115]
	v_mfma_f32_16x16x32_bf16 v[100:103], v[164:167], v[204:207], v[100:103]
	v_mfma_f32_16x16x32_bf16 v[96:99], v[172:175], v[204:207], v[96:99]
	v_mfma_f32_16x16x32_bf16 v[84:87], v[164:167], v[212:215], v[84:87]
	v_mfma_f32_16x16x32_bf16 v[80:83], v[172:175], v[212:215], v[80:83]
	v_mfma_f32_16x16x32_bf16 v[68:71], v[164:167], v[220:223], v[68:71]
	v_mfma_f32_16x16x32_bf16 v[64:67], v[172:175], v[220:223], v[64:67]
	s_setprio 0
	s_barrier
	s_add_i32 s36, s59, s39
	v_lshl_add_u64 v[176:177], v[176:177], 0, s[14:15]
	s_mov_b32 m0, s36
	ds_read_b128 v[192:195], v190 offset:49152
	ds_read_b128 v[196:199], v190 offset:50176
	ds_read_b128 v[200:203], v190 offset:51200
	ds_read_b128 v[204:207], v190 offset:52224
	ds_read_b128 v[208:211], v190 offset:53248
	ds_read_b128 v[212:215], v190 offset:54272
	ds_read_b128 v[216:219], v190 offset:55296
	ds_read_b128 v[220:223], v190 offset:56320
	global_load_lds_dwordx4 v[176:177], off
	s_add_i32 m0, s36, 0x2000
	s_add_u32 s34, s34, 0xb0080
	v_lshl_add_u64 v[176:177], v[224:225], 0, s[14:15]
	s_addc_u32 s35, s35, 0
	s_add_i32 s36, s60, s39
	global_load_lds_dwordx4 v[176:177], off
	v_lshl_add_u64 v[176:177], s[34:35], 0, v[130:131]
	s_mov_b32 m0, s36
	s_nop 0
	global_load_lds_dwordx4 v[176:177], off
	v_lshl_add_u64 v[176:177], s[34:35], 0, v[134:135]
	s_add_i32 m0, s36, 0x2000
	s_nop 0
	global_load_lds_dwordx4 v[176:177], off
	v_lshl_add_u64 v[176:177], v[226:227], 0, s[14:15]
	s_mov_b32 m0, s47
	s_nop 0
	global_load_lds_dwordx4 v[176:177], off
	v_lshl_add_u64 v[176:177], v[228:229], 0, s[14:15]
	s_mov_b32 m0, s48
	s_nop 0
	global_load_lds_dwordx4 v[176:177], off
	s_waitcnt vmcnt(8)
	s_waitcnt lgkmcnt(0)
	v_mfma_f32_16x16x32_bf16 v[60:63], v[144:147], v[192:195], v[60:63]
	v_mfma_f32_16x16x32_bf16 v[56:59], v[152:155], v[192:195], v[56:59]
	v_mfma_f32_16x16x32_bf16 v[44:47], v[144:147], v[200:203], v[44:47]
	v_mfma_f32_16x16x32_bf16 v[40:43], v[152:155], v[200:203], v[40:43]
	v_mfma_f32_16x16x32_bf16 v[28:31], v[144:147], v[208:211], v[28:31]
	v_mfma_f32_16x16x32_bf16 v[24:27], v[152:155], v[208:211], v[24:27]
	v_mfma_f32_16x16x32_bf16 v[12:15], v[144:147], v[216:219], v[12:15]
	v_mfma_f32_16x16x32_bf16 v[8:11], v[152:155], v[216:219], v[8:11]
	s_barrier
	s_setprio 1
	v_mfma_f32_16x16x32_bf16 v[60:63], v[148:151], v[196:199], v[60:63]
	v_mfma_f32_16x16x32_bf16 v[56:59], v[156:159], v[196:199], v[56:59]
	v_mfma_f32_16x16x32_bf16 v[44:47], v[148:151], v[204:207], v[44:47]
	v_mfma_f32_16x16x32_bf16 v[40:43], v[156:159], v[204:207], v[40:43]
	v_mfma_f32_16x16x32_bf16 v[28:31], v[148:151], v[212:215], v[28:31]
	v_mfma_f32_16x16x32_bf16 v[24:27], v[156:159], v[212:215], v[24:27]
	v_mfma_f32_16x16x32_bf16 v[12:15], v[148:151], v[220:223], v[12:15]
	v_mfma_f32_16x16x32_bf16 v[8:11], v[156:159], v[220:223], v[8:11]
	s_setprio 0
	s_setprio 1
	v_mfma_f32_16x16x32_bf16 v[52:55], v[160:163], v[192:195], v[52:55]
	v_mfma_f32_16x16x32_bf16 v[48:51], v[168:171], v[192:195], v[48:51]
	v_mfma_f32_16x16x32_bf16 v[36:39], v[160:163], v[200:203], v[36:39]
	v_mfma_f32_16x16x32_bf16 v[32:35], v[168:171], v[200:203], v[32:35]
	v_mfma_f32_16x16x32_bf16 v[20:23], v[160:163], v[208:211], v[20:23]
	v_mfma_f32_16x16x32_bf16 v[16:19], v[168:171], v[208:211], v[16:19]
	v_mfma_f32_16x16x32_bf16 v[4:7], v[160:163], v[216:219], v[4:7]
	v_mfma_f32_16x16x32_bf16 v[0:3], v[168:171], v[216:219], v[0:3]
	v_mfma_f32_16x16x32_bf16 v[52:55], v[164:167], v[196:199], v[52:55]
	v_mfma_f32_16x16x32_bf16 v[48:51], v[172:175], v[196:199], v[48:51]
	v_mfma_f32_16x16x32_bf16 v[36:39], v[164:167], v[204:207], v[36:39]
	v_mfma_f32_16x16x32_bf16 v[32:35], v[172:175], v[204:207], v[32:35]
	v_mfma_f32_16x16x32_bf16 v[20:23], v[164:167], v[212:215], v[20:23]
	v_mfma_f32_16x16x32_bf16 v[16:19], v[172:175], v[212:215], v[16:19]
	v_mfma_f32_16x16x32_bf16 v[4:7], v[164:167], v[220:223], v[4:7]
	v_mfma_f32_16x16x32_bf16 v[0:3], v[172:175], v[220:223], v[0:3]
	s_setprio 0
	s_barrier
	s_add_i32 s58, s58, 2
	s_add_u32 s4, s4, 0x100
	s_addc_u32 s5, s5, 0
	s_add_u32 s23, s23, 0x100
	s_addc_u32 s27, s27, 0
	s_cmp_gt_u32 s58, 41
	s_cbranch_scc0 .LBB0_1061
	s_and_b64 vcc, exec, s[16:17]
	s_cbranch_vccz .LBB0_1064
	s_barrier
